# diff S block: dropped the full lgkm drain that the counted waits made redundant
# baseline (speedup 1.0000x reference)
; DI float ex2(float x) { return __builtin_amdgcn_exp2f(x); }
; #define SB0 __builtin_amdgcn_sched_barrier(0)
; template <bool MASKED, class MF>
; DI void flash_update(f32x4 (&s)[4], float scl, float& mx, float& ls, f32x4 (&o)[8], MF maskfn, bool lane_on) {
;   float tmax = -1e30f;
; #pragma unroll
;   for (int kt = 0; kt < 4; ++kt)
; #pragma unroll
;     for (int i = 0; i < 4; ++i) {
;       if (MASKED) { if (maskfn(kt, i)) s[kt][i] = -1e30f; }
;       tmax = fmaxf(tmax, s[kt][i]);
;     }
;   tmax = rowmax4(tmax);
;   if (!lane_on) tmax = -1e30f;
;   const float th = 8.f / scl;
;   if (__any(tmax > mx + th)) {
;     const float mnew = fmaxf(mx, tmax);
;     const float alpha = ex2((mx - mnew) * scl);
;     ls *= alpha;
; #pragma unroll
;     for (int dt = 0; dt < 8; ++dt) o[dt] *= alpha;
;     mx = mnew;
;   }
; DI void ldk2m(bf16x8 (&k)[2], const char* Kb, int m, int kt, int lr, int quad) {
; #pragma unroll
;   for (int kk = 0; kk < 2; ++kk) k[kk] = *(const bf16x8*)(Kb + (kt * 16 + lr) * 256 + (((m * 8 + kk * 4 + quad) ^ lr) << 4));
; }
; DI void diff_S2(f32x4 (&s0)[4], f32x4 (&s1)[4], const char* Kb, const char* Vb, int m, const bf16x8 (&q0)[2], const bf16x8 (&q1)[2],
;                 bf16x8 (&v0)[4], bf16x8 (&v1)[4], int lr, int quad) {
;   bf16x8 f0[2], f1[2], f2[2], f3[2];
;   ldk2m(f0, Kb, m, 0, lr, quad); ldk2m(f1, Kb, m, 1, lr, quad); SB0;
;   ldk2m(f2, Kb, m, 2, lr, quad); s0[0] = mma2(f0, q0); s1[0] = mma2(f0, q1); SB0;
;   ldk2m(f3, Kb, m, 3, lr, quad); s0[1] = mma2(f1, q0); s1[1] = mma2(f1, q1); SB0;
;   ldv4(v0, Vb, 0, lr, quad); s0[2] = mma2(f2, q0); s1[2] = mma2(f2, q1); SB0;
;   ldv4(v1, Vb, 1, lr, quad); s0[3] = mma2(f3, q0); s1[3] = mma2(f3, q1); SB0;
; }
.LBB0_571:
	s_cmp_eq_u32 s7, s63
	s_cbranch_scc1 .LBB0_582
	s_or_b32 s4, s7, s65
	s_lshl_b32 s6, s4, 6
	v_cmp_le_u32_e32 vcc, s6, v211
	s_and_saveexec_b64 s[48:49], vcc
	s_cbranch_execz .LBB0_570
	s_lshl_b32 s4, s7, 15
	s_add_i32 s67, s66, s4
	v_add_u32_e32 v0, s67, v212
	v_add_u32_e32 v28, v0, v214
	v_add_u32_e32 v29, v0, v215
	ds_read_b128 v[0:3], v28
	ds_read_b128 v[4:7], v28 offset:4096
	ds_read_b128 v[8:11], v29
	ds_read_b128 v[12:15], v29 offset:4096
	s_or_b32 s4, s6, 63
	v_cmp_le_u32_e32 vcc, s4, v207
	ds_read_b128 v[16:19], v28 offset:8192
	ds_read_b128 v[20:23], v29 offset:8192
	s_setprio 1
	s_waitcnt lgkmcnt(5)
	v_mfma_f32_16x16x32_bf16 v[24:27], v[0:3], v[96:99], 0
	s_waitcnt lgkmcnt(3)
	v_mfma_f32_16x16x32_bf16 v[172:175], v[8:11], v[100:103], v[24:27]
	s_setprio 0
	s_setprio 1
	v_mfma_f32_16x16x32_bf16 v[0:3], v[0:3], v[104:107], 0
	v_mfma_f32_16x16x32_bf16 v[156:159], v[8:11], v[108:111], v[0:3]
	s_setprio 0
	s_nop 5
	ds_read_b128 v[0:3], v28 offset:12288
	ds_read_b128 v[8:11], v29 offset:12288
	s_setprio 1
	v_mfma_f32_16x16x32_bf16 v[24:27], v[4:7], v[96:99], 0
	s_waitcnt lgkmcnt(4)
	v_mfma_f32_16x16x32_bf16 v[164:167], v[12:15], v[100:103], v[24:27]
	s_setprio 0
	s_setprio 1
	v_mfma_f32_16x16x32_bf16 v[4:7], v[4:7], v[104:107], 0
	v_mfma_f32_16x16x32_bf16 v[148:151], v[12:15], v[108:111], v[4:7]
	s_setprio 0
	v_add3_u32 v12, s67, v217, v216
	ds_read_b128 v[140:143], v12 offset:16384
	ds_read_b128 v[136:139], v12 offset:18432
	ds_read_b128 v[128:131], v12 offset:20480
	ds_read_b128 v[120:123], v12 offset:22528
	s_setprio 1
	s_waitcnt lgkmcnt(7)
	v_mfma_f32_16x16x32_bf16 v[4:7], v[16:19], v[96:99], 0
	s_waitcnt lgkmcnt(6)
	v_mfma_f32_16x16x32_bf16 v[168:171], v[20:23], v[100:103], v[4:7]
	s_setprio 0
	s_setprio 1
	v_mfma_f32_16x16x32_bf16 v[4:7], v[16:19], v[104:107], 0
	v_mfma_f32_16x16x32_bf16 v[152:155], v[20:23], v[108:111], v[4:7]
	s_setprio 0
	ds_read_b128 v[132:135], v12 offset:24576
	ds_read_b128 v[124:127], v12 offset:26624
	ds_read_b128 v[116:119], v12 offset:28672
	ds_read_b128 v[112:115], v12 offset:30720
	s_setprio 1
	s_waitcnt lgkmcnt(9)
	v_mfma_f32_16x16x32_bf16 v[4:7], v[0:3], v[96:99], 0
	s_waitcnt lgkmcnt(8)
	v_mfma_f32_16x16x32_bf16 v[160:163], v[8:11], v[100:103], v[4:7]
	s_setprio 0
	s_setprio 1
	v_mfma_f32_16x16x32_bf16 v[0:3], v[0:3], v[104:107], 0
	v_mfma_f32_16x16x32_bf16 v[144:147], v[8:11], v[108:111], v[0:3]
	s_setprio 0
	v_add_f32_e32 v232, 0x40b17218, v220
	s_and_saveexec_b64 s[4:5], vcc
	s_xor_b64 s[4:5], exec, s[4:5]
	s_cbranch_execz .LBB0_579
	s_nop 1
	v_max3_f32 v0, v172, s53, v173
	v_max3_f32 v0, v0, v174, v175
	v_max3_f32 v0, v0, v164, v165
	v_max3_f32 v0, v0, v166, v167
	v_max3_f32 v0, v0, v168, v169
	v_max3_f32 v0, v0, v170, v171
	v_max3_f32 v0, v0, v160, v161
	v_max3_f32 v0, v0, v162, v163
	v_mov_b32_e32 v1, v0
	s_nop 1
	v_permlane16_swap_b32_e32 v0, v1
	v_max_f32_e32 v1, v1, v1
	v_max_f32_e32 v0, v0, v0
	v_max_f32_e32 v0, v0, v1
	v_mov_b32_e32 v1, v0
	s_nop 1
	v_permlane32_swap_b32_e32 v0, v1
	v_max_f32_e32 v1, v1, v1
	v_max_f32_e32 v0, v0, v0
	v_max_f32_e32 v0, v0, v1
	v_cmp_gt_f32_e32 vcc, v0, v232
	s_cbranch_vccz .LBB0_576
	v_max_f32_e32 v0, v0, v0
	v_max_f32_e32 v1, v220, v220
	v_max_f32_e32 v1, v1, v0
	v_sub_f32_e32 v0, v220, v1
	v_mul_f32_e32 v0, 0x3fb8aa3b, v0
	v_exp_f32_e32 v0, v0
	v_mov_b32_e32 v220, v1
	v_mul_f32_e32 v213, v213, v0
	v_pk_mul_f32 v[94:95], v[94:95], v[0:1] op_sel_hi:[1,0]
	v_pk_mul_f32 v[92:93], v[92:93], v[0:1] op_sel_hi:[1,0]
	v_pk_mul_f32 v[90:91], v[90:91], v[0:1] op_sel_hi:[1,0]
	v_pk_mul_f32 v[88:89], v[88:89], v[0:1] op_sel_hi:[1,0]
	v_pk_mul_f32 v[86:87], v[86:87], v[0:1] op_sel_hi:[1,0]
	v_pk_mul_f32 v[84:85], v[84:85], v[0:1] op_sel_hi:[1,0]
	v_pk_mul_f32 v[82:83], v[82:83], v[0:1] op_sel_hi:[1,0]
	v_pk_mul_f32 v[80:81], v[80:81], v[0:1] op_sel_hi:[1,0]
	v_pk_mul_f32 v[78:79], v[78:79], v[0:1] op_sel_hi:[1,0]
	v_pk_mul_f32 v[76:77], v[76:77], v[0:1] op_sel_hi:[1,0]
	v_pk_mul_f32 v[74:75], v[74:75], v[0:1] op_sel_hi:[1,0]
	v_pk_mul_f32 v[72:73], v[72:73], v[0:1] op_sel_hi:[1,0]
	v_pk_mul_f32 v[70:71], v[70:71], v[0:1] op_sel_hi:[1,0]
	v_pk_mul_f32 v[68:69], v[68:69], v[0:1] op_sel_hi:[1,0]
	v_pk_mul_f32 v[66:67], v[66:67], v[0:1] op_sel_hi:[1,0]
	v_pk_mul_f32 v[64:65], v[64:65], v[0:1] op_sel_hi:[1,0]
